# poll loops: s_sleep 32 between polls (was 10)
# baseline (speedup 1.0000x reference)
; DI unsigned xb_ld(unsigned* p)              { return __hip_atomic_load(p, __ATOMIC_RELAXED, __HIP_MEMORY_SCOPE_AGENT); }
; DI unsigned xb_add(unsigned* p, unsigned v) { return __hip_atomic_fetch_add(p, v, __ATOMIC_RELAXED, __HIP_MEMORY_SCOPE_AGENT); }
; #define XB_SPIN(cond, bar) do { unsigned _sp = 0; while (cond) { __builtin_amdgcn_s_sleep(1); \
;     if ((++_sp & 255u) == 0u) { if (xb_ld(&(bar)[XB_TMO])) break; if (_sp > XB_SPIN_CAP) { atomicAdd(&(bar)[XB_TMO], 1u); break; } } } } while (0)
; DI void xcd_barrier(unsigned* bar, volatile __attribute__((address_space(3))) unsigned* st) {
;     ...
;             else XB_SPIN(xb_ld(&bar[XB_TOPGEN]) == tg, bar);
;             __builtin_amdgcn_fence(__ATOMIC_ACQUIRE, "agent");
;             xb_add(&bar[XB_XGEN(x)], 1u);
;             asm volatile("s_waitcnt vmcnt(0)" ::: "memory");
;         } else {
;             XB_SPIN(xb_ld(&bar[XB_XGEN(x)]) == gen, bar);
.Lnlf_p1:
	global_load_dword v3, v2, s[70:71] offset:1280 sc1
	s_waitcnt vmcnt(0)
	v_cmp_lt_u32_e32 vcc, v3, v4
	s_cbranch_vccz .Lnlf_d1
	s_sleep 32
	s_branch .Lnlf_p1
